# attention loop now has one workgroup barrier per KV tile: both V write-after-read barriers removed (V staging write deferred past barrier B; second half-step parks V in dead bf16-P registers)
# speedup vs baseline: 1.0023x; 1.0023x over previous
; __device__ __forceinline__ void partialSM(f32x16& p0, f32x16& p1, float& m_reg, float& mn, float& alpha) {
;     ...
;     const float mnL = -mn * C2;
;     for (int r = 0; r < 16; ++r) p0[r] = fmaf(p0[r], C2, mnL); for (int r = 0; r < 16; ++r) p1[r] = fmaf(p1[r], C2, mnL);
;     for (int r = 0; r < 16; ++r) p0[r] = __builtin_amdgcn_exp2f(p0[r]);
; __device__ __forceinline__ void attn_block(const BlockRef& cur, const BlockRef& nxt, int skv, int W, char* lds, Seam& S) {
;     ...
;     for (int t = 1; t + 1 < NT; t += 2) {
;         HALF_STEP(pB0, pB1, mnB, alB, pA0, pA1, alA, t, 1, 0, 0);
;         HALF_STEP(pA0, pA1, mnA, alA, pB0, pB1, alB, t + 1, 0, 1, 1);
.LBB0_534:
	v_cndmask_b32_e64 v172, v152, v228, s[0:1]
	v_mul_f32_e32 v158, 0xbdd53b94, v172
	s_waitcnt vmcnt(2)
	v_mov_b32_e32 v162, v158
	v_fmamk_f32 v112, v112, 0x3dd53b94, v158
	v_fmamk_f32 v113, v113, 0x3dd53b94, v158
	v_fmamk_f32 v114, v114, 0x3dd53b94, v158
	v_fmamk_f32 v115, v115, 0x3dd53b94, v158
	v_fmamk_f32 v116, v116, 0x3dd53b94, v158
	v_fmamk_f32 v117, v117, 0x3dd53b94, v158
	v_fmamk_f32 v118, v118, 0x3dd53b94, v158
	v_fmamk_f32 v119, v119, 0x3dd53b94, v158
	v_fmamk_f32 v120, v120, 0x3dd53b94, v158
	v_fmamk_f32 v121, v121, 0x3dd53b94, v158
	v_fmamk_f32 v122, v122, 0x3dd53b94, v158
	v_fmamk_f32 v157, v123, 0x3dd53b94, v158
	v_fmamk_f32 v159, v124, 0x3dd53b94, v158
	v_fmamk_f32 v160, v125, 0x3dd53b94, v158
	v_fmamk_f32 v161, v126, 0x3dd53b94, v158
	v_fmac_f32_e32 v162, 0x3dd53b94, v127
	v_exp_f32_e32 v153, v112
	v_exp_f32_e32 v155, v113
	v_exp_f32_e32 v127, v114
	v_exp_f32_e32 v154, v115
	v_exp_f32_e32 v126, v116
	v_exp_f32_e32 v152, v117
	v_exp_f32_e32 v124, v118
	v_exp_f32_e32 v125, v119
	v_exp_f32_e32 v120, v120
	v_exp_f32_e32 v123, v121
	v_exp_f32_e32 v118, v122
	v_exp_f32_e32 v121, v157
	v_exp_f32_e32 v116, v159
	v_exp_f32_e32 v122, v160
	v_exp_f32_e32 v117, v161
	v_exp_f32_e32 v119, v162
	v_pk_fma_f32 v[114:115], v[96:97], s[18:19], v[158:159] op_sel_hi:[1,0,0]
	v_add_f32_e32 v96, v224, v225
	v_fmac_f32_e32 v96, v216, v217
	v_add_f32_e32 v217, v231, v232
	s_addk_i32 s55, 0x80
	s_add_i32 s54, s54, 2
	v_pk_fma_f32 v[110:111], v[110:111], s[18:19], v[158:159] op_sel_hi:[1,0,0]
	v_pk_fma_f32 v[108:109], v[108:109], s[18:19], v[158:159] op_sel_hi:[1,0,0]
	v_pk_fma_f32 v[106:107], v[106:107], s[18:19], v[158:159] op_sel_hi:[1,0,0]
	v_pk_fma_f32 v[104:105], v[104:105], s[18:19], v[158:159] op_sel_hi:[1,0,0]
	v_pk_fma_f32 v[102:103], v[102:103], s[18:19], v[158:159] op_sel_hi:[1,0,0]
	v_pk_fma_f32 v[100:101], v[100:101], s[18:19], v[158:159] op_sel_hi:[1,0,0]
	v_pk_fma_f32 v[112:113], v[98:99], s[18:19], v[158:159] op_sel_hi:[1,0,0]
	v_fmac_f32_e32 v217, v96, v227
	s_cmp_ge_i32 s54, s66
	v_add_u32_e32 v191, 0xffffff80, v191
	v_mov_b32_e32 v216, v156
	s_waitcnt lgkmcnt(0)
	s_barrier
	s_add_i32 s100, s54, -1
	s_cmp_lt_i32 s100, s66
	s_cbranch_scc0 .Latt_vdef_skip
	ds_write_b128 v218, v[176:179] offset:16384
	ds_write_b128 v219, v[180:183] offset:16384
.Latt_vdef_skip:
	s_cmp_ge_i32 s54, s66
	s_cbranch_scc1 .LBB0_551

; __device__ __forceinline__ void partialSM(f32x16& p0, f32x16& p1, float& m_reg, float& mn, float& alpha) {
;     float pmax = p0[0]; for (int r = 1; r < 16; ++r) pmax = fmaxf(pmax, p0[r]); for (int r = 0; r < 16; ++r) pmax = fmaxf(pmax, p1[r]);
;     { auto rr = __builtin_amdgcn_permlane32_swap(__float_as_uint(pmax), __float_as_uint(pmax), false, false);
;       pmax = fmaxf(__uint_as_float(rr[0]), __uint_as_float(rr[1])); }
;     constexpr float C2 = 1.4426950408889634f * SCALE;
;     if (__builtin_expect(__all((pmax - m_reg) * SCALE <= THR), 1)) { mn = m_reg; alpha = 1.f; }
;     else { mn = fmaxf(m_reg, pmax); alpha = __builtin_amdgcn_exp2f((m_reg - mn) * C2); m_reg = mn; }
.LBB0_545:
	v_max_f32_e32 v172, v113, v113
	v_max_f32_e32 v173, v112, v112
	v_max_f32_e32 v172, v173, v172
	v_max3_f32 v172, v172, v114, v115
	v_max3_f32 v172, v172, v116, v117
	v_max3_f32 v172, v172, v118, v119
	v_max3_f32 v172, v172, v120, v121
	v_max3_f32 v172, v172, v122, v123
	v_max3_f32 v172, v172, v124, v125
	v_max3_f32 v172, v172, v126, v127
	v_max3_f32 v172, v172, v96, v97
	v_max3_f32 v172, v172, v98, v99
	v_max3_f32 v172, v172, v100, v101
	v_max3_f32 v172, v172, v102, v103
	v_max3_f32 v172, v172, v104, v105
	v_max3_f32 v172, v172, v106, v107
	v_max3_f32 v172, v172, v108, v109
	v_max3_f32 v172, v172, v110, v111
	v_mov_b32_e32 v173, v172
	s_nop 1
	v_permlane32_swap_b32_e32 v172, v173
	v_max_f32_e32 v173, v173, v173
	v_max_f32_e32 v172, v172, v172
	v_max_f32_e32 v172, v172, v173
	v_sub_f32_e32 v173, v172, v228
	v_mul_f32_e32 v173, 0x3d93cd3a, v173
	v_cmp_ge_f32_e32 vcc, s57, v173
	s_cmp_eq_u64 vcc, exec
	s_cselect_b64 s[0:1], -1, 0
	s_andn2_b64 vcc, exec, s[48:49]
	s_cbranch_vccnz .LBB0_547
	s_waitcnt vmcnt(0)
	s_waitcnt vmcnt(2)
	ds_write_b128 v203, v[160:163] offset:57344
	s_waitcnt vmcnt(1)
	ds_write_b128 v203, v[164:167] offset:57472
	s_waitcnt vmcnt(0)
	ds_write_b128 v203, v[168:171] offset:57600
	v_mov_b32_e32 v176, v152
	v_mov_b32_e32 v177, v153
	v_mov_b32_e32 v178, v154
	v_mov_b32_e32 v179, v155
	v_mov_b32_e32 v180, v156
	v_mov_b32_e32 v181, v157
	v_mov_b32_e32 v182, v158
	v_mov_b32_e32 v183, v159

; __global__ void __launch_bounds__(NWAVES * 64, 2) fwd_kernel(Args a) {
	.amdhsa_kernel _Z10fwd_kernel4Args
		.amdhsa_group_segment_fixed_size 0
		.amdhsa_private_segment_fixed_size 0
		.amdhsa_kernarg_size 432
		.amdhsa_user_sgpr_count 2
		.amdhsa_user_sgpr_dispatch_ptr 0
		.amdhsa_user_sgpr_queue_ptr 0
		.amdhsa_user_sgpr_kernarg_segment_ptr 1
		.amdhsa_user_sgpr_dispatch_id 0
		.amdhsa_user_sgpr_kernarg_preload_length 0
		.amdhsa_user_sgpr_kernarg_preload_offset 0
		.amdhsa_user_sgpr_private_segment_size 0
		.amdhsa_uses_dynamic_stack 0
		.amdhsa_enable_private_segment 0
		.amdhsa_system_sgpr_workgroup_id_x 1
		.amdhsa_system_sgpr_workgroup_id_y 0
		.amdhsa_system_sgpr_workgroup_id_z 0
		.amdhsa_system_sgpr_workgroup_info 0
		.amdhsa_system_vgpr_workitem_id 2
		.amdhsa_next_free_vgpr 255
		.amdhsa_next_free_sgpr 102
		.amdhsa_accum_offset 256
		.amdhsa_reserve_vcc 1
		.amdhsa_float_round_mode_32 0
		.amdhsa_float_round_mode_16_64 0
		.amdhsa_float_denorm_mode_32 3
		.amdhsa_float_denorm_mode_16_64 3
		.amdhsa_dx10_clamp 1
		.amdhsa_ieee_mode 1
		.amdhsa_fp16_overflow 0
		.amdhsa_tg_split 0
		.amdhsa_exception_fp_ieee_invalid_op 0
		.amdhsa_exception_fp_denorm_src 0
		.amdhsa_exception_fp_ieee_div_zero 0
		.amdhsa_exception_fp_ieee_overflow 0
		.amdhsa_exception_fp_ieee_underflow 0
		.amdhsa_exception_fp_ieee_inexact 0
		.amdhsa_exception_int_div_zero 0
	.end_amdhsa_kernel

; __global__ void __launch_bounds__(NWAVES * 64, 2) fwd_kernel(Args a) {
amdhsa.kernels:
  - .agpr_count:     0
    .args:
      - .offset:         0
        .size:           176
        .value_kind:     by_value
      - .offset:         176
        .size:           4
        .value_kind:     hidden_block_count_x
      - .offset:         180
        .size:           4
        .value_kind:     hidden_block_count_y
      - .offset:         184
        .size:           4
        .value_kind:     hidden_block_count_z
      - .offset:         188
        .size:           2
        .value_kind:     hidden_group_size_x
      - .offset:         190
        .size:           2
        .value_kind:     hidden_group_size_y
      - .offset:         192
        .size:           2
        .value_kind:     hidden_group_size_z
      - .offset:         194
        .size:           2
        .value_kind:     hidden_remainder_x
      - .offset:         196
        .size:           2
        .value_kind:     hidden_remainder_y
      - .offset:         198
        .size:           2
        .value_kind:     hidden_remainder_z
      - .offset:         216
        .size:           8
        .value_kind:     hidden_global_offset_x
      - .offset:         224
        .size:           8
        .value_kind:     hidden_global_offset_y
      - .offset:         232
        .size:           8
        .value_kind:     hidden_global_offset_z
      - .offset:         240
        .size:           2
        .value_kind:     hidden_grid_dims
      - .offset:         264
        .size:           8
        .value_kind:     hidden_multigrid_sync_arg
      - .offset:         296
        .size:           4
        .value_kind:     hidden_dynamic_lds_size
    .group_segment_fixed_size: 0
    .kernarg_segment_align: 8
    .kernarg_segment_size: 432
    .language:       OpenCL C
    .language_version:
      - 2
      - 0
    .max_flat_workgroup_size: 512
    .name:           _Z10fwd_kernel4Args
    .private_segment_fixed_size: 0
    .sgpr_count:     108
    .sgpr_spill_count: 27
    .symbol:         _Z10fwd_kernel4Args.kd
    .uniform_work_group_size: 1
    .uses_dynamic_stack: false
    .vgpr_count:     255
    .vgpr_spill_count: 0
    .wavefront_size: 64
